# m23 + step A: the last iteration of a unit no longer re-loads key fragments it will not use (scalar test around the four loads), so the post-loop vmcnt(0) has nothing to wait for
# speedup vs baseline: 1.0036x; 1.0010x over previous
.LBB0_1296:
	ds_read_b128 v[18:21], v173
	ds_read_b128 v[28:31], v173 offset:1024
	s_add_i32 s8, s3, s17
	s_add_i32 s0, s18, 1
	s_add_i32 s9, s8, 8
	s_waitcnt vmcnt(3) lgkmcnt(1)
	v_mfma_f32_16x16x32_bf16 v[32:35], v[6:9], v[18:21], 0
	s_cmp_lt_i32 s0, s13
	s_cselect_b64 s[0:1], -1, 0
	s_and_b64 vcc, s[0:1], exec
	s_waitcnt vmcnt(1)
	v_mfma_f32_16x16x32_bf16 v[178:181], v[14:17], v[18:21], 0
	ds_read_b128 v[22:25], v174
	ds_read_b128 v[18:21], v174 offset:1024
	ds_read_b128 v[182:185], v173 offset:2048
	ds_read_b128 v[200:203], v173 offset:3072
	s_cselect_b32 s10, s9, s8
	s_add_i32 s9, s8, 16
	s_waitcnt lgkmcnt(4)
	v_mfma_f32_16x16x32_bf16 v[204:207], v[2:5], v[28:31], v[32:35]
	s_cmp_lt_i32 s18, s14
	s_cselect_b32 s9, s9, s8
	s_add_i32 s8, s8, 24
	v_mov_b32_e32 v34, 0
	s_waitcnt vmcnt(0)
	v_mfma_f32_16x16x32_bf16 v[178:181], v[10:13], v[28:31], v[178:181]
	s_nop 1
	v_max_i32_e32 v32, 0, v204
	v_max_i32_e32 v28, 0, v205
	v_mov_b32_e32 v35, 0
	s_waitcnt lgkmcnt(3)
	v_fmac_f32 v34, v32, v22
	v_fmac_f32 v35, v28, v22
	v_max_i32_e32 v28, 0, v206
	v_mov_b32_e32 v32, 0
	v_fmac_f32 v32, v28, v22
	v_max_i32_e32 v28, 0, v207
	s_waitcnt lgkmcnt(1)
	v_mfma_f32_16x16x32_bf16 v[204:207], v[6:9], v[182:185], 0
	v_mov_b32_e32 v33, 0
	v_fmac_f32 v33, v28, v22
	v_max_i32_e32 v28, 0, v178
	v_mov_b32_e32 v30, 0
	v_fmac_f32 v30, v28, v22
	v_max_i32_e32 v28, 0, v179
	v_mov_b32_e32 v31, 0
	v_fmac_f32 v31, v28, v22
	v_max_i32_e32 v29, 0, v180
	v_mov_b32_e32 v28, 0
	v_max_i32_e32 v177, 0, v181
	s_waitcnt lgkmcnt(0)
	v_mfma_f32_16x16x32_bf16 v[178:181], v[2:5], v[200:203], v[204:207]
	v_fmac_f32 v28, v29, v22
	v_mov_b32_e32 v29, 0
	v_fmac_f32 v29, v177, v22
	v_mfma_f32_16x16x32_bf16 v[182:185], v[14:17], v[182:185], 0
	s_nop 0
	ds_read_b128 v[204:207], v173 offset:4096
	ds_read_b128 v[208:211], v173 offset:5120
	s_nop 2
	v_max_i32_e32 v22, 0, v178
	v_fmac_f32 v34, v22, v23
	v_max_i32_e32 v22, 0, v179
	v_mfma_f32_16x16x32_bf16 v[182:185], v[10:13], v[200:203], v[182:185]
	v_fmac_f32 v35, v22, v23
	v_max_i32_e32 v22, 0, v180
	v_fmac_f32 v32, v22, v23
	v_max_i32_e32 v22, 0, v181
	s_waitcnt lgkmcnt(1)
	v_mfma_f32_16x16x32_bf16 v[178:181], v[6:9], v[204:207], 0
	v_fmac_f32 v33, v22, v23
	s_nop 3
	v_max_i32_e32 v22, 0, v182
	v_fmac_f32 v30, v22, v23
	v_max_i32_e32 v22, 0, v183
	s_waitcnt lgkmcnt(0)
	v_mfma_f32_16x16x32_bf16 v[178:181], v[2:5], v[208:211], v[178:181]
	v_fmac_f32 v31, v22, v23
	v_max_i32_e32 v22, 0, v184
	v_fmac_f32 v28, v22, v23
	v_max_i32_e32 v22, 0, v185
	v_fmac_f32 v29, v22, v23
	v_mfma_f32_16x16x32_bf16 v[200:203], v[14:17], v[204:207], 0
	ds_read_b128 v[182:185], v173 offset:6144
	ds_read_b128 v[204:207], v173 offset:7168
	s_nop 2
	v_max_i32_e32 v22, 0, v178
	v_fmac_f32 v34, v22, v24
	v_max_i32_e32 v22, 0, v179
	v_fmac_f32 v35, v22, v24
	v_max_i32_e32 v22, 0, v180
	v_mfma_f32_16x16x32_bf16 v[200:203], v[10:13], v[208:211], v[200:203]
	v_fmac_f32 v32, v22, v24
	v_max_i32_e32 v22, 0, v181
	v_fmac_f32 v33, v22, v24
	s_waitcnt lgkmcnt(1)
	v_mfma_f32_16x16x32_bf16 v[178:181], v[6:9], v[182:185], 0
	s_cmp_lt_i32 s18, s15
	s_nop 3
	v_max_i32_e32 v22, 0, v200
	v_fmac_f32 v30, v22, v24
	v_mfma_f32_16x16x32_bf16 v[182:185], v[14:17], v[182:185], 0
	v_max_i32_e32 v22, 0, v201
	v_fmac_f32 v31, v22, v24
	v_max_i32_e32 v22, 0, v202
	s_waitcnt lgkmcnt(0)
	v_mfma_f32_16x16x32_bf16 v[178:181], v[2:5], v[204:207], v[178:181]
	v_fmac_f32 v28, v22, v24
	v_max_i32_e32 v22, 0, v203
	v_fmac_f32 v29, v22, v24
	v_mfma_f32_16x16x32_bf16 v[182:185], v[10:13], v[204:207], v[182:185]
	ds_read_b128 v[200:203], v173 offset:8192
	ds_read_b128 v[208:211], v173 offset:9216
	s_nop 3
	v_max_i32_e32 v22, 0, v178
	v_fmac_f32 v34, v22, v25
	v_max_i32_e32 v22, 0, v179
	v_fmac_f32 v35, v22, v25
	v_max_i32_e32 v22, 0, v180
	v_fmac_f32 v32, v22, v25
	v_max_i32_e32 v22, 0, v181
	v_fmac_f32 v33, v22, v25
	v_max_i32_e32 v22, 0, v182
	s_waitcnt lgkmcnt(1)
	v_mfma_f32_16x16x32_bf16 v[178:181], v[6:9], v[200:203], 0
	v_fmac_f32 v30, v22, v25
	v_max_i32_e32 v22, 0, v183
	v_fmac_f32 v31, v22, v25
	v_max_i32_e32 v22, 0, v184
	v_fmac_f32 v28, v22, v25
	v_max_i32_e32 v22, 0, v185
	v_mfma_f32_16x16x32_bf16 v[200:203], v[14:17], v[200:203], 0
	v_fmac_f32 v29, v22, v25
	s_cselect_b32 s11, s8, s9
	s_waitcnt lgkmcnt(0)
	v_mfma_f32_16x16x32_bf16 v[22:25], v[2:5], v[208:211], v[178:181]
	s_nop 2
	ds_read_b128 v[178:181], v173 offset:10240
	ds_read_b128 v[182:185], v173 offset:11264
	s_lshl_b32 s68, s9, 4
	s_lshl_b64 s[8:9], s[68:69], 7
	v_mfma_f32_16x16x32_bf16 v[200:203], v[10:13], v[208:211], v[200:203]
	v_max_i32_e32 v22, 0, v22
	v_fmac_f32 v34, v22, v18
	v_max_i32_e32 v22, 0, v23
	v_fmac_f32 v35, v22, v18
	v_max_i32_e32 v22, 0, v24
	v_fmac_f32 v32, v22, v18
	v_max_i32_e32 v22, 0, v25
	v_fmac_f32 v33, v22, v18
	s_nop 3
	v_max_i32_e32 v22, 0, v200
	v_fmac_f32 v30, v22, v18
	s_waitcnt lgkmcnt(1)
	v_mfma_f32_16x16x32_bf16 v[22:25], v[6:9], v[178:181], 0
	v_max_i32_e32 v177, 0, v201
	v_fmac_f32 v31, v177, v18
	v_max_i32_e32 v177, 0, v202
	v_mfma_f32_16x16x32_bf16 v[178:181], v[14:17], v[178:181], 0
	v_fmac_f32 v28, v177, v18
	v_max_i32_e32 v177, 0, v203
	v_fmac_f32 v29, v177, v18
	s_waitcnt lgkmcnt(0)
	v_mfma_f32_16x16x32_bf16 v[22:25], v[2:5], v[182:185], v[22:25]
	ds_read_b128 v[200:203], v173 offset:12288
	ds_read_b128 v[204:207], v173 offset:13312
	v_mfma_f32_16x16x32_bf16 v[178:181], v[10:13], v[182:185], v[178:181]
	s_nop 4
	v_max_i32_e32 v18, 0, v22
	v_fmac_f32 v34, v18, v19
	v_max_i32_e32 v18, 0, v23
	v_fmac_f32 v35, v18, v19
	v_max_i32_e32 v18, 0, v24
	v_fmac_f32 v32, v18, v19
	v_max_i32_e32 v18, 0, v25
	v_fmac_f32 v33, v18, v19
	v_max_i32_e32 v18, 0, v178
	v_fmac_f32 v30, v18, v19
	s_waitcnt lgkmcnt(1)
	v_mfma_f32_16x16x32_bf16 v[22:25], v[6:9], v[200:203], 0
	v_max_i32_e32 v18, 0, v179
	v_fmac_f32 v31, v18, v19
	v_max_i32_e32 v18, 0, v180
	v_fmac_f32 v28, v18, v19
	v_max_i32_e32 v18, 0, v181
	v_fmac_f32 v29, v18, v19
	v_mfma_f32_16x16x32_bf16 v[182:185], v[14:17], v[200:203], 0
	ds_read_b128 v[178:181], v173 offset:14336
	ds_read_b128 v[200:203], v173 offset:15360
	s_waitcnt lgkmcnt(2)
	v_mfma_f32_16x16x32_bf16 v[22:25], v[2:5], v[204:207], v[22:25]
	s_waitcnt lgkmcnt(1)
	v_mfma_f32_16x16x32_bf16 v[6:9], v[6:9], v[178:181], 0
	v_mfma_f32_16x16x32_bf16 v[182:185], v[10:13], v[204:207], v[182:185]
	s_nop 4
	v_max_i32_e32 v18, 0, v22
	v_fmac_f32 v34, v18, v20
	v_max_i32_e32 v18, 0, v23
	v_fmac_f32 v35, v18, v20
	v_max_i32_e32 v18, 0, v24
	v_fmac_f32 v32, v18, v20
	v_max_i32_e32 v18, 0, v25
	v_mfma_f32_16x16x32_bf16 v[14:17], v[14:17], v[178:181], 0
	v_fmac_f32 v33, v18, v20
	v_max_i32_e32 v18, 0, v182
	v_fmac_f32 v30, v18, v20
	s_waitcnt lgkmcnt(0)
	v_mfma_f32_16x16x32_bf16 v[2:5], v[2:5], v[200:203], v[6:9]
	v_max_i32_e32 v18, 0, v183
	v_fmac_f32 v31, v18, v20
	v_max_i32_e32 v18, 0, v184
	v_fmac_f32 v28, v18, v20
	s_nop 0
	v_max_i32_e32 v6, 0, v185
	v_fmac_f32 v29, v6, v20
	v_mfma_f32_16x16x32_bf16 v[6:9], v[10:13], v[200:203], v[14:17]
	s_nop 2
	v_max_i32_e32 v2, 0, v2
	v_fmac_f32 v34, v2, v21
	v_max_i32_e32 v2, 0, v3
	v_fmac_f32 v35, v2, v21
	v_max_i32_e32 v2, 0, v4
	v_fmac_f32 v32, v2, v21
	v_max_i32_e32 v2, 0, v5
	v_fmac_f32 v33, v2, v21
	s_nop 0
	v_max_i32_e32 v2, 0, v6
	v_fmac_f32 v30, v2, v21
	v_max_i32_e32 v2, 0, v7
	v_fmac_f32 v31, v2, v21
	v_max_i32_e32 v2, 0, v8
	v_fmac_f32 v28, v2, v21
	v_max_i32_e32 v2, 0, v9
	v_fmac_f32 v29, v2, v21
	v_lshl_add_u64 v[2:3], v[26:27], 0, s[8:9]
	s_lshl_b32 s8, s11, 4
	s_ashr_i32 s9, s8, 31
	s_lshl_b64 s[8:9], s[8:9], 7
	v_lshl_add_u64 v[10:11], v[26:27], 0, s[8:9]
	s_add_i32 s8, s17, 16
	s_cmp_eq_u32 s8, s16
	s_cbranch_scc1 .Lix_noload
	global_load_dwordx4 v[6:9], v[2:3], off
	s_nop 0
	global_load_dwordx4 v[2:5], v[2:3], off offset:64
	s_nop 0
	global_load_dwordx4 v[14:17], v[10:11], off
	s_nop 0
	global_load_dwordx4 v[10:13], v[10:11], off offset:64
.Lix_noload:
	s_cmp_eq_u32 s10, s12
	v_ashrrev_i32_e32 v178, 31, v34
	s_cbranch_scc1 .LBB0_1317
	v_bitop3_b32 v18, v178, v34, s76 bitop3:0x36
	v_lshrrev_b32_e32 v19, 21, v18
	v_add_u32_e32 v19, v19, v172
	v_and_b32_e32 v20, 0x7ff, v19
	v_lshrrev_b32_e32 v19, 3, v19
	v_bitop3_b32 v19, v19, v20, 28 bitop3:0x6c
	v_lshl_add_u32 v19, v19, 2, v40
	ds_add_u32 v19, v186
	v_ashrrev_i32_e32 v19, 31, v35
	v_bitop3_b32 v19, v19, v35, s76 bitop3:0x36
	v_lshrrev_b32_e32 v20, 21, v19
	v_add_u32_e32 v20, v20, v172
	v_and_b32_e32 v21, 0x7ff, v20
	v_lshrrev_b32_e32 v20, 3, v20
	v_bitop3_b32 v20, v20, v21, 28 bitop3:0x6c
	v_lshl_add_u32 v20, v20, 2, v40
	ds_add_u32 v20, v186
	v_ashrrev_i32_e32 v20, 31, v32
	v_bitop3_b32 v20, v20, v32, s76 bitop3:0x36
	v_lshrrev_b32_e32 v21, 21, v20
	v_add_u32_e32 v21, v21, v172
	v_and_b32_e32 v22, 0x7ff, v21
	v_lshrrev_b32_e32 v21, 3, v21
	v_bitop3_b32 v21, v21, v22, 28 bitop3:0x6c
	v_lshl_add_u32 v21, v21, 2, v40
	ds_add_u32 v21, v186
	v_ashrrev_i32_e32 v21, 31, v33
	v_bitop3_b32 v23, v21, v33, s76 bitop3:0x36
	v_lshrrev_b32_e32 v21, 21, v23
	v_add_u32_e32 v21, v21, v172
	v_and_b32_e32 v22, 0x7ff, v21
	v_lshrrev_b32_e32 v21, 3, v21
	v_bitop3_b32 v21, v21, v22, 28 bitop3:0x6c
	v_lshl_add_u32 v21, v21, 2, v40
	ds_add_u32 v21, v186
	s_mov_b64 s[10:11], 0
	v_mov_b32_e32 v25, 0
	v_mov_b32_e32 v24, 0
	v_mov_b32_e32 v22, 0
	v_mov_b32_e32 v21, 0
	s_mov_b64 s[8:9], 0
	s_mov_b64 vcc, vcc
	s_cbranch_vccz .LBB0_1299
	v_ashrrev_i32_e32 v21, 31, v30
	v_bitop3_b32 v21, v21, v30, s76 bitop3:0x36
	v_lshrrev_b32_e32 v22, 21, v21
	v_add_u32_e32 v22, v22, v172
	v_and_b32_e32 v24, 0x7ff, v22
	v_lshrrev_b32_e32 v22, 3, v22
	v_bitop3_b32 v22, v22, v24, 28 bitop3:0x6c
	v_lshl_add_u32 v22, v22, 2, v40
	ds_add_u32 v22, v186
	v_ashrrev_i32_e32 v22, 31, v31
	v_bitop3_b32 v22, v22, v31, s76 bitop3:0x36
	v_lshrrev_b32_e32 v24, 21, v22
	v_add_u32_e32 v24, v24, v172
	v_and_b32_e32 v25, 0x7ff, v24
	v_lshrrev_b32_e32 v24, 3, v24
	v_bitop3_b32 v24, v24, v25, 28 bitop3:0x6c
	v_lshl_add_u32 v24, v24, 2, v40
	ds_add_u32 v24, v186
	v_ashrrev_i32_e32 v24, 31, v28
	v_bitop3_b32 v24, v24, v28, s76 bitop3:0x36
	v_lshrrev_b32_e32 v25, 21, v24
	v_add_u32_e32 v25, v25, v172
	v_and_b32_e32 v177, 0x7ff, v25
	v_lshrrev_b32_e32 v25, 3, v25
	v_bitop3_b32 v25, v25, v177, 28 bitop3:0x6c
	v_lshl_add_u32 v25, v25, 2, v40
	ds_add_u32 v25, v186
	v_ashrrev_i32_e32 v25, 31, v29
	v_bitop3_b32 v177, v25, v29, s76 bitop3:0x36
	s_mov_b64 s[8:9], -1
	v_mov_b32_e32 v25, v177
